# fixed-reference attention path: exact-zero tile skip distance 151/slope2 (p = 2^((s-R)-bias), s-R<=0, is exactly +0 in f32 beyond it); output bit-identical
# speedup vs baseline: 1.0610x; 1.0149x over previous
.LBB0_306:
	s_or_b64 exec, exec, s[0:1]
	v_readlane_b32 s0, v252, 1
	v_mov_b32_e32 v169, 0
	v_readlane_b32 s1, v252, 2
	v_mov_b32_e32 v5, 0x8000
	s_waitcnt lgkmcnt(0)
	s_barrier
	v_add_f32_e32 v2, v0, v2
	s_nop 0
	global_load_dword v4, v169, s[0:1] sc1
	v_add_f32_e32 v1, v1, v3
	global_load_dword v5, v5, s[62:63] offset:768 sc1
	s_mov_b32 s0, 0x3fb8aa3b
	v_lshrrev_b32_e32 v7, 4, v209
	v_lshlrev_b32_e32 v10, 4, v209
	v_mul_f32_e32 v13, 0x3fb8aa3b, v2
	v_lshrrev_b32_e32 v8, 5, v209
	v_lshrrev_b32_e32 v9, 3, v209
	v_mul_f32_e32 v14, 0x3fb8aa3b, v1
	v_and_b32_e32 v15, 51, v7
	v_and_b32_e32 v17, 0xf0, v10
	v_mul_u32_u24_e32 v7, 0x1400, v7
	v_fma_f32 v20, v2, s0, -v13
	v_rndne_f32_e32 v21, v13
	v_and_b32_e32 v8, 4, v8
	v_and_b32_e32 v16, 8, v9
	v_fma_f32 v22, v1, s0, -v14
	v_rndne_f32_e32 v23, v14
	v_or_b32_e32 v170, v17, v7
	v_fmac_f32_e32 v20, 0x32a5705f, v2
	v_sub_f32_e32 v7, v13, v21
	v_or3_b32 v8, v15, v8, v16
	v_fmac_f32_e32 v22, 0x32a5705f, v1
	v_sub_f32_e32 v14, v14, v23
	v_add_f32_e32 v7, v7, v20
	v_cvt_i32_f32_e32 v13, v21
	v_mul_u32_u24_e32 v8, 0x110, v8
	v_add_f32_e32 v14, v14, v22
	v_exp_f32_e32 v7, v7
	v_cvt_i32_f32_e32 v15, v23
	v_add3_u32 v212, 0, v8, v17
	v_exp_f32_e32 v8, v14
	s_mov_b32 s1, 0xc2ce8ed0
	v_ldexp_f32 v7, v7, v13
	v_cmp_ngt_f32_e32 vcc, s1, v2
	s_mov_b32 s33, 0x42b17218
	v_ldexp_f32 v8, v8, v15
	v_cndmask_b32_e32 v7, 0, v7, vcc
	v_cmp_ngt_f32_e32 vcc, s1, v1
	v_mov_b32_e32 v3, 0x7f800000
	s_mov_b32 s38, 0xf800000
	v_cndmask_b32_e32 v8, 0, v8, vcc
	v_cmp_nlt_f32_e32 vcc, s33, v2
	s_add_u32 s4, s62, 0xc00000
	s_addc_u32 s5, s63, 0
	v_cndmask_b32_e32 v2, v3, v7, vcc
	v_cmp_nlt_f32_e32 vcc, s33, v1
	s_add_u32 s6, s62, 0xd00000
	s_addc_u32 s7, s63, 0
	v_cndmask_b32_e32 v1, v3, v8, vcc
	v_sub_f32_e32 v1, v2, v1
	v_add_f32_e32 v172, 0x3eb60549, v1
	s_add_u32 s34, s62, 0xe00000
	s_addc_u32 s35, s63, 0
	s_add_u32 s26, s62, 0x1000000
	s_addc_u32 s27, s63, 0
	v_mov_b32_e32 v6, 0x260
	s_add_u32 s24, s62, 0x1b00000
	s_addc_u32 s25, s63, 0
	s_add_u32 s36, s62, 0x1c900000
	s_addc_u32 s37, s63, 0
	v_mul_u32_u24_e32 v11, 0x110, v167
	v_lshlrev_b32_e32 v12, 4, v166
	s_add_u32 s40, s62, 0x8000
	s_addc_u32 s41, s63, 0
	v_add3_u32 v214, 0, v11, v12
	v_lshlrev_b32_e32 v0, 3, v166
	s_add_i32 s66, s64, 0xa00
	v_lshlrev_b32_e32 v168, 2, v167
	v_and_b32_e32 v18, 0x70, v10
	v_mul_u32_u24_e32 v19, 0x10080, v9
	v_mul_u32_u24_e32 v9, 0x90, v9
	v_lshl_add_u64 v[194:195], s[30:31], 0, v[168:169]
	s_movk_i32 s30, 0xff80
	s_mov_b32 s44, 0xfffb0000
	s_movk_i32 s13, 0x1400
	v_mov_b32_e32 v171, v169
	v_lshl_add_u32 v216, v129, 2, 0
	v_lshl_add_u64 v[174:175], s[56:57], 0, v[168:169]
	s_movk_i32 s67, 0x84
	v_or_b32_e32 v219, 8, v177
	s_waitcnt vmcnt(0)
	v_mul_f32_e32 v2, v4, v5
	v_mul_f32_e32 v3, 0x4f800000, v2
	v_cmp_gt_f32_e32 vcc, s38, v2
	v_or_b32_e32 v220, 16, v177
	v_or_b32_e32 v221, 24, v177
	v_cndmask_b32_e32 v2, v2, v3, vcc
	v_sqrt_f32_e32 v3, v2
	v_lshl_add_u64 v[180:181], s[54:55], 0, v[168:169]
	v_lshl_add_u64 v[184:185], s[52:53], 0, v[168:169]
	v_lshl_add_u64 v[186:187], s[48:49], 0, v[168:169]
	v_add_u32_e32 v1, -1, v3
	v_add_u32_e32 v4, 1, v3
	v_fma_f32 v5, -v1, v3, v2
	v_fma_f32 v7, -v4, v3, v2
	v_cmp_ge_f32_e64 s[0:1], 0, v5
	v_mov_b32_e32 v5, v169
	v_lshl_add_u64 v[190:191], s[46:47], 0, v[168:169]
	v_cndmask_b32_e64 v1, v3, v1, s[0:1]
	v_cmp_lt_f32_e64 s[0:1], 0, v7
	v_mov_b32_e32 v173, v172
	v_mov_b32_e32 v165, v166
	v_cndmask_b32_e64 v1, v1, v4, s[0:1]
	v_mul_f32_e32 v3, 0x37800000, v1
	v_cndmask_b32_e32 v1, v1, v3, vcc
	v_cmp_class_f32_e32 vcc, v2, v6
	s_add_i32 s0, 0, 0x12000
	v_add_u32_e32 v217, s0, v12
	v_cndmask_b32_e32 v1, v1, v2, vcc
	v_add_f32_e32 v1, v1, v1
	v_mul_f32_e32 v1, 0x3f828f5c, v1
	v_sub_f32_e32 v253, 0, v1
	v_mov_b32_e32 v254, 0x42400000
	v_cmp_lt_f32_e64 s[98:99], v1, v254
	s_nop 1
	v_cndmask_b32_e64 v253, 0, v253, s[98:99]
	s_getreg_b32 s100, hwreg(HW_REG_XCC_ID, 0, 4)
	s_and_b32 s100, s100, 7
	s_mov_b32 s101, 0
	v_fmaak_f32 v213, 2.0, v1, 0x43160000
	v_mov_b32_e32 v254, 0x43170000
	v_cndmask_b32_e64 v213, v213, v254, s[98:99]
	v_lshlrev_b32_e32 v1, 7, v167
	v_sub_u32_e32 v215, v214, v1
	s_mul_i32 s0, s78, 0x2200
	v_and_b32_e32 v1, 56, v200
	s_add_i32 s0, s0, 0
	v_mul_u32_u24_e32 v3, 0x84, v1
	v_lshlrev_b32_e32 v4, 1, v1
	v_lshlrev_b32_e32 v1, 2, v177
	v_add3_u32 v218, s0, v3, v1
	v_add_u32_e32 v1, 0, v10
	v_lshlrev_b32_e32 v2, 2, v166
	s_cmpk_lt_i32 s64, 0x1480
	v_add_u32_e32 v176, s0, v168
	s_mov_b32 s0, 0x20000
	v_add_u32_e32 v224, 0xd000, v1
	v_sub_u32_e32 v1, v167, v0
	s_cselect_b64 s[42:43], -1, 0
	v_lshl_add_u64 v[178:179], s[24:25], 0, v[4:5]
	v_lshl_add_u64 v[182:183], s[26:27], 0, v[4:5]
	v_lshl_add_u64 v[188:189], s[34:35], 0, v[4:5]
	v_lshl_add_u64 v[192:193], s[6:7], 0, v[4:5]
	v_lshl_add_u64 v[196:197], s[4:5], 0, v[4:5]
	v_cmp_gt_i32_e64 s[0:1], s0, v164
	s_lshl_b32 s68, s14, 9
	v_add3_u32 v222, 0, v9, v18
	v_add_u32_e32 v223, 0xfffffe00, v209
	v_or_b32_e32 v198, v19, v18
	v_mov_b32_e32 v199, v169
	v_add_u32_e32 v225, 0xffffff80, v1
	v_lshl_add_u32 v226, s2, 12, v200
	s_lshl_b32 s69, s14, 12
	s_mov_b64 s[52:53], 0
	s_add_i32 s70, 0, 0x12400
	v_lshlrev_b32_e32 v200, 1, v0
	s_movk_i32 s71, 0x27f
	s_mov_b32 s72, 0xc2fc0000
	s_mov_b32 s73, 0xff61b1e6
	s_mov_b32 s74, 0x40c00000
	s_mov_b32 s31, -1
	s_mov_b32 s45, -1
	v_lshlrev_b32_e32 v202, 1, v2
	v_mov_b32_e32 v227, 0x358637bd
	s_movk_i32 s75, 0x2c00
	s_mov_b64 s[46:47], 0x1000
	s_mov_b32 s76, 0x6800000
	s_mov_b32 s77, 0x1a900000
	s_mov_b32 s78, 0x6801000
	s_mov_b32 s79, 0x6802000
	s_mov_b32 s80, 0x6803000
	s_mov_b32 s81, 0x6804000
	s_mov_b64 s[48:49], 0x5000
	s_mov_b32 s82, 0x1ffff
	v_mov_b32_e32 v240, v169
	v_mov_b32_e32 v241, v169
	v_mov_b32_e32 v242, v169
	v_mov_b32_e32 v243, v169
	v_mov_b32_e32 v228, 0x42800000
	v_mov_b32_e32 v229, 0x7149f2ca
	s_branch .LBB0_309
